# on top of previous: in the three GEMM K-loops s_setprio 1 moved before the opening barrier, s_setprio 0 after the closing barrier, mid-segment prio flip pair and redundant post-barrier lgkmcnt(0) remo
# speedup vs baseline: 1.0142x; 1.0084x over previous
.LBB0_221:
	s_add_u32 s42, s10, 0x4000
	s_addc_u32 s43, s11, 0
	s_cmp_eq_u32 s67, 12
	s_cselect_b32 s50, s19, s42
	s_cselect_b32 s51, s9, s43
	s_cselect_b32 s46, s54, s62
	s_cselect_b32 s47, s17, s63
	s_add_u32 s42, s50, 0x8000
	s_addc_u32 s43, s51, 0
	s_add_i32 s57, 0, 0x10000
	s_add_i32 s60, 0, 0x14000
	v_add_u32_e32 v70, s57, v199
	v_add_u32_e32 v158, s60, v199
	ds_read_b128 v[50:53], v70
	ds_read_b128 v[54:57], v70 offset:1024
	ds_read_b128 v[66:69], v70 offset:2048
	ds_read_b128 v[70:73], v70 offset:3072
	ds_read_b128 v[146:149], v158
	ds_read_b128 v[150:153], v158 offset:1024
	ds_read_b128 v[154:157], v158 offset:2048
	ds_read_b128 v[158:161], v158 offset:3072
	v_lshl_add_u64 v[188:189], s[10:11], 0, v[176:177]
	s_add_i32 m0, s45, 0xc000
	ds_read_b128 v[180:183], v241
	ds_read_b128 v[184:187], v241 offset:1024
	ds_read_b128 v[202:205], v241 offset:2048
	ds_read_b128 v[206:209], v241 offset:3072
	ds_read_b128 v[210:213], v241 offset:4096
	ds_read_b128 v[214:217], v241 offset:5120
	ds_read_b128 v[218:221], v241 offset:6144
	ds_read_b128 v[244:247], v241 offset:7168
	global_load_lds_dwordx4 v[188:189], off
	v_lshl_add_u64 v[188:189], s[10:11], 0, v[178:179]
	s_add_i32 m0, s45, 0xe000
	s_nop 0
	global_load_lds_dwordx4 v[188:189], off
	s_waitcnt vmcnt(8)
	s_waitcnt lgkmcnt(0)
	s_setprio 1
	s_barrier
	v_mfma_f32_16x16x32_bf16 v[142:145], v[50:53], v[180:183], v[142:145]
	v_mfma_f32_16x16x32_bf16 v[138:141], v[66:69], v[180:183], v[138:141]
	v_mfma_f32_16x16x32_bf16 v[126:129], v[50:53], v[202:205], v[126:129]
	v_mfma_f32_16x16x32_bf16 v[122:125], v[66:69], v[202:205], v[122:125]
	v_mfma_f32_16x16x32_bf16 v[110:113], v[50:53], v[210:213], v[110:113]
	v_mfma_f32_16x16x32_bf16 v[106:109], v[66:69], v[210:213], v[106:109]
	v_mfma_f32_16x16x32_bf16 v[94:97], v[50:53], v[218:221], v[94:97]
	v_mfma_f32_16x16x32_bf16 v[90:93], v[66:69], v[218:221], v[90:93]
	v_mfma_f32_16x16x32_bf16 v[142:145], v[54:57], v[184:187], v[142:145]
	v_mfma_f32_16x16x32_bf16 v[138:141], v[70:73], v[184:187], v[138:141]
	v_mfma_f32_16x16x32_bf16 v[126:129], v[54:57], v[206:209], v[126:129]
	v_mfma_f32_16x16x32_bf16 v[122:125], v[70:73], v[206:209], v[122:125]
	v_mfma_f32_16x16x32_bf16 v[110:113], v[54:57], v[214:217], v[110:113]
	v_mfma_f32_16x16x32_bf16 v[106:109], v[70:73], v[214:217], v[106:109]
	v_mfma_f32_16x16x32_bf16 v[94:97], v[54:57], v[244:247], v[94:97]
	v_mfma_f32_16x16x32_bf16 v[90:93], v[70:73], v[244:247], v[90:93]
	v_mfma_f32_16x16x32_bf16 v[134:137], v[146:149], v[180:183], v[134:137]
	v_mfma_f32_16x16x32_bf16 v[130:133], v[154:157], v[180:183], v[130:133]
	v_mfma_f32_16x16x32_bf16 v[118:121], v[146:149], v[202:205], v[118:121]
	v_mfma_f32_16x16x32_bf16 v[114:117], v[154:157], v[202:205], v[114:117]
	v_mfma_f32_16x16x32_bf16 v[102:105], v[146:149], v[210:213], v[102:105]
	v_mfma_f32_16x16x32_bf16 v[98:101], v[154:157], v[210:213], v[98:101]
	v_mfma_f32_16x16x32_bf16 v[86:89], v[146:149], v[218:221], v[86:89]
	v_mfma_f32_16x16x32_bf16 v[82:85], v[154:157], v[218:221], v[82:85]
	v_mfma_f32_16x16x32_bf16 v[134:137], v[150:153], v[184:187], v[134:137]
	v_mfma_f32_16x16x32_bf16 v[130:133], v[158:161], v[184:187], v[130:133]
	v_mfma_f32_16x16x32_bf16 v[118:121], v[150:153], v[206:209], v[118:121]
	v_mfma_f32_16x16x32_bf16 v[114:117], v[158:161], v[206:209], v[114:117]
	v_mfma_f32_16x16x32_bf16 v[102:105], v[150:153], v[214:217], v[102:105]
	v_mfma_f32_16x16x32_bf16 v[98:101], v[158:161], v[214:217], v[98:101]
	v_mfma_f32_16x16x32_bf16 v[86:89], v[150:153], v[244:247], v[86:89]
	v_mfma_f32_16x16x32_bf16 v[82:85], v[158:161], v[244:247], v[82:85]
	s_barrier
	s_setprio 0
	s_add_i32 s57, s57, s69
	v_lshl_add_u64 v[188:189], s[46:47], 0, v[164:165]
	s_mov_b32 m0, s57
	ds_read_b128 v[180:183], v241 offset:16384
	ds_read_b128 v[184:187], v241 offset:17408
	ds_read_b128 v[202:205], v241 offset:18432
	ds_read_b128 v[206:209], v241 offset:19456
	ds_read_b128 v[210:213], v241 offset:20480
	ds_read_b128 v[214:217], v241 offset:21504
	ds_read_b128 v[218:221], v241 offset:22528
	ds_read_b128 v[244:247], v241 offset:23552
	global_load_lds_dwordx4 v[188:189], off
	s_add_i32 m0, s57, 0x2000
	s_add_u32 s94, s46, 0x40000
	v_lshl_add_u64 v[222:223], s[46:47], 0, v[168:169]
	s_addc_u32 s95, s47, 0
	s_add_i32 s57, s60, s69
	global_load_lds_dwordx4 v[222:223], off
	v_lshl_add_u64 v[234:235], s[94:95], 0, v[164:165]
	s_mov_b32 m0, s57
	s_nop 0
	global_load_lds_dwordx4 v[234:235], off
	v_lshl_add_u64 v[234:235], s[94:95], 0, v[168:169]
	s_add_i32 m0, s57, 0x2000
	s_nop 0
	global_load_lds_dwordx4 v[234:235], off
	v_lshl_add_u64 v[234:235], s[50:51], 0, v[162:163]
	s_mov_b32 m0, s45
	s_nop 0
	global_load_lds_dwordx4 v[234:235], off
	v_lshl_add_u64 v[234:235], s[50:51], 0, v[166:167]
	s_mov_b32 m0, s3
	s_nop 0
	global_load_lds_dwordx4 v[234:235], off
	s_waitcnt vmcnt(8)
	s_waitcnt lgkmcnt(0)
	s_setprio 1
	s_barrier
	v_mfma_f32_16x16x32_bf16 v[78:81], v[50:53], v[180:183], v[78:81]
	v_mfma_f32_16x16x32_bf16 v[74:77], v[66:69], v[180:183], v[74:77]
	v_mfma_f32_16x16x32_bf16 v[46:49], v[50:53], v[202:205], v[46:49]
	v_mfma_f32_16x16x32_bf16 v[42:45], v[66:69], v[202:205], v[42:45]
	v_mfma_f32_16x16x32_bf16 v[30:33], v[50:53], v[210:213], v[30:33]
	v_mfma_f32_16x16x32_bf16 v[26:29], v[66:69], v[210:213], v[26:29]
	v_mfma_f32_16x16x32_bf16 v[14:17], v[50:53], v[218:221], v[14:17]
	v_mfma_f32_16x16x32_bf16 v[10:13], v[66:69], v[218:221], v[10:13]
	v_mfma_f32_16x16x32_bf16 v[78:81], v[54:57], v[184:187], v[78:81]
	v_mfma_f32_16x16x32_bf16 v[74:77], v[70:73], v[184:187], v[74:77]
	v_mfma_f32_16x16x32_bf16 v[46:49], v[54:57], v[206:209], v[46:49]
	v_mfma_f32_16x16x32_bf16 v[42:45], v[70:73], v[206:209], v[42:45]
	v_mfma_f32_16x16x32_bf16 v[30:33], v[54:57], v[214:217], v[30:33]
	v_mfma_f32_16x16x32_bf16 v[26:29], v[70:73], v[214:217], v[26:29]
	v_mfma_f32_16x16x32_bf16 v[14:17], v[54:57], v[244:247], v[14:17]
	v_mfma_f32_16x16x32_bf16 v[10:13], v[70:73], v[244:247], v[10:13]
	v_mfma_f32_16x16x32_bf16 v[38:41], v[146:149], v[202:205], v[38:41]
	v_mfma_f32_16x16x32_bf16 v[34:37], v[154:157], v[202:205], v[34:37]
	v_mfma_f32_16x16x32_bf16 v[22:25], v[146:149], v[210:213], v[22:25]
	v_mfma_f32_16x16x32_bf16 v[18:21], v[154:157], v[210:213], v[18:21]
	v_mfma_f32_16x16x32_bf16 v[6:9], v[146:149], v[218:221], v[6:9]
	v_mfma_f32_16x16x32_bf16 v[2:5], v[154:157], v[218:221], v[2:5]
	v_mfma_f32_16x16x32_bf16 v[50:53], v[146:149], v[180:183], v[62:65]
	v_mfma_f32_16x16x32_bf16 v[54:57], v[154:157], v[180:183], v[58:61]
	v_mfma_f32_16x16x32_bf16 v[38:41], v[150:153], v[206:209], v[38:41]
	v_mfma_f32_16x16x32_bf16 v[34:37], v[158:161], v[206:209], v[34:37]
	v_mfma_f32_16x16x32_bf16 v[22:25], v[150:153], v[214:217], v[22:25]
	v_mfma_f32_16x16x32_bf16 v[18:21], v[158:161], v[214:217], v[18:21]
	v_mfma_f32_16x16x32_bf16 v[6:9], v[150:153], v[244:247], v[6:9]
	v_mfma_f32_16x16x32_bf16 v[2:5], v[158:161], v[244:247], v[2:5]
	v_mfma_f32_16x16x32_bf16 v[50:53], v[150:153], v[184:187], v[50:53]
	v_mfma_f32_16x16x32_bf16 v[54:57], v[158:161], v[184:187], v[54:57]
	s_barrier
	s_setprio 0
	s_add_i32 s57, 0, 0x18000
	s_add_i32 s60, 0, 0x1c000
	v_add_u32_e32 v70, s57, v199
	v_add_u32_e32 v158, s60, v199
	ds_read_b128 v[58:61], v70
	ds_read_b128 v[62:65], v70 offset:1024
	ds_read_b128 v[66:69], v70 offset:2048
	ds_read_b128 v[70:73], v70 offset:3072
	ds_read_b128 v[146:149], v158
	ds_read_b128 v[150:153], v158 offset:1024
	ds_read_b128 v[154:157], v158 offset:2048
	ds_read_b128 v[158:161], v158 offset:3072
	s_add_u32 s50, s50, 0x4000
	s_addc_u32 s51, s51, 0
	s_mov_b32 m0, s31
	v_lshl_add_u64 v[234:235], s[50:51], 0, v[162:163]
	ds_read_b128 v[180:183], v241 offset:32768
	ds_read_b128 v[184:187], v241 offset:33792
	ds_read_b128 v[202:205], v241 offset:34816
	ds_read_b128 v[206:209], v241 offset:35840
	ds_read_b128 v[210:213], v241 offset:36864
	ds_read_b128 v[214:217], v241 offset:37888
	ds_read_b128 v[218:221], v241 offset:38912
	ds_read_b128 v[244:247], v241 offset:39936
	global_load_lds_dwordx4 v[234:235], off
	v_lshl_add_u64 v[234:235], s[50:51], 0, v[166:167]
	s_mov_b32 m0, s33
	s_nop 0
	global_load_lds_dwordx4 v[234:235], off
	s_waitcnt vmcnt(8)
	s_waitcnt lgkmcnt(0)
	s_setprio 1
	s_barrier
	v_mfma_f32_16x16x32_bf16 v[142:145], v[58:61], v[180:183], v[142:145]
	v_mfma_f32_16x16x32_bf16 v[138:141], v[66:69], v[180:183], v[138:141]
	v_mfma_f32_16x16x32_bf16 v[126:129], v[58:61], v[202:205], v[126:129]
	v_mfma_f32_16x16x32_bf16 v[122:125], v[66:69], v[202:205], v[122:125]
	v_mfma_f32_16x16x32_bf16 v[110:113], v[58:61], v[210:213], v[110:113]
	v_mfma_f32_16x16x32_bf16 v[106:109], v[66:69], v[210:213], v[106:109]
	v_mfma_f32_16x16x32_bf16 v[94:97], v[58:61], v[218:221], v[94:97]
	v_mfma_f32_16x16x32_bf16 v[90:93], v[66:69], v[218:221], v[90:93]
	v_mfma_f32_16x16x32_bf16 v[142:145], v[62:65], v[184:187], v[142:145]
	v_mfma_f32_16x16x32_bf16 v[138:141], v[70:73], v[184:187], v[138:141]
	v_mfma_f32_16x16x32_bf16 v[126:129], v[62:65], v[206:209], v[126:129]
	v_mfma_f32_16x16x32_bf16 v[122:125], v[70:73], v[206:209], v[122:125]
	v_mfma_f32_16x16x32_bf16 v[110:113], v[62:65], v[214:217], v[110:113]
	v_mfma_f32_16x16x32_bf16 v[106:109], v[70:73], v[214:217], v[106:109]
	v_mfma_f32_16x16x32_bf16 v[94:97], v[62:65], v[244:247], v[94:97]
	v_mfma_f32_16x16x32_bf16 v[90:93], v[70:73], v[244:247], v[90:93]
	v_mfma_f32_16x16x32_bf16 v[134:137], v[146:149], v[180:183], v[134:137]
	v_mfma_f32_16x16x32_bf16 v[130:133], v[154:157], v[180:183], v[130:133]
	v_mfma_f32_16x16x32_bf16 v[118:121], v[146:149], v[202:205], v[118:121]
	v_mfma_f32_16x16x32_bf16 v[114:117], v[154:157], v[202:205], v[114:117]
	v_mfma_f32_16x16x32_bf16 v[102:105], v[146:149], v[210:213], v[102:105]
	v_mfma_f32_16x16x32_bf16 v[98:101], v[154:157], v[210:213], v[98:101]
	v_mfma_f32_16x16x32_bf16 v[86:89], v[146:149], v[218:221], v[86:89]
	v_mfma_f32_16x16x32_bf16 v[82:85], v[154:157], v[218:221], v[82:85]
	v_mfma_f32_16x16x32_bf16 v[134:137], v[150:153], v[184:187], v[134:137]
	v_mfma_f32_16x16x32_bf16 v[130:133], v[158:161], v[184:187], v[130:133]
	v_mfma_f32_16x16x32_bf16 v[118:121], v[150:153], v[206:209], v[118:121]
	v_mfma_f32_16x16x32_bf16 v[114:117], v[158:161], v[206:209], v[114:117]
	v_mfma_f32_16x16x32_bf16 v[102:105], v[150:153], v[214:217], v[102:105]
	v_mfma_f32_16x16x32_bf16 v[98:101], v[158:161], v[214:217], v[98:101]
	v_mfma_f32_16x16x32_bf16 v[86:89], v[150:153], v[244:247], v[86:89]
	v_mfma_f32_16x16x32_bf16 v[82:85], v[158:161], v[244:247], v[82:85]
	s_barrier
	s_setprio 0
	s_add_i32 s50, s57, s69
	v_lshl_add_u64 v[188:189], v[188:189], 0, s[64:65]
	s_mov_b32 m0, s50
	ds_read_b128 v[180:183], v241 offset:49152
	ds_read_b128 v[184:187], v241 offset:50176
	ds_read_b128 v[202:205], v241 offset:51200
	ds_read_b128 v[206:209], v241 offset:52224
	ds_read_b128 v[210:213], v241 offset:53248
	ds_read_b128 v[214:217], v241 offset:54272
	ds_read_b128 v[218:221], v241 offset:55296
	ds_read_b128 v[244:247], v241 offset:56320
	global_load_lds_dwordx4 v[188:189], off
	s_add_i32 m0, s50, 0x2000
	s_add_u32 s46, s46, 0x40080
	v_lshl_add_u64 v[188:189], v[222:223], 0, s[64:65]
	s_addc_u32 s47, s47, 0
	s_add_i32 s50, s60, s69
	global_load_lds_dwordx4 v[188:189], off
	v_lshl_add_u64 v[188:189], s[46:47], 0, v[164:165]
	s_mov_b32 m0, s50
	s_nop 0
	global_load_lds_dwordx4 v[188:189], off
	v_lshl_add_u64 v[188:189], s[46:47], 0, v[168:169]
	s_add_i32 m0, s50, 0x2000
	s_nop 0
	global_load_lds_dwordx4 v[188:189], off
	v_lshl_add_u64 v[188:189], s[42:43], 0, v[162:163]
	s_mov_b32 m0, s29
	s_nop 0
	global_load_lds_dwordx4 v[188:189], off
	v_lshl_add_u64 v[188:189], s[42:43], 0, v[166:167]
	s_mov_b32 m0, s21
	s_nop 0
	global_load_lds_dwordx4 v[188:189], off
	s_waitcnt vmcnt(8)
	s_waitcnt lgkmcnt(0)
	s_setprio 1
	s_barrier
	v_mfma_f32_16x16x32_bf16 v[78:81], v[58:61], v[180:183], v[78:81]
	v_mfma_f32_16x16x32_bf16 v[74:77], v[66:69], v[180:183], v[74:77]
	v_mfma_f32_16x16x32_bf16 v[46:49], v[58:61], v[202:205], v[46:49]
	v_mfma_f32_16x16x32_bf16 v[42:45], v[66:69], v[202:205], v[42:45]
	v_mfma_f32_16x16x32_bf16 v[30:33], v[58:61], v[210:213], v[30:33]
	v_mfma_f32_16x16x32_bf16 v[26:29], v[66:69], v[210:213], v[26:29]
	v_mfma_f32_16x16x32_bf16 v[14:17], v[58:61], v[218:221], v[14:17]
	v_mfma_f32_16x16x32_bf16 v[10:13], v[66:69], v[218:221], v[10:13]
	v_mfma_f32_16x16x32_bf16 v[78:81], v[62:65], v[184:187], v[78:81]
	v_mfma_f32_16x16x32_bf16 v[74:77], v[70:73], v[184:187], v[74:77]
	v_mfma_f32_16x16x32_bf16 v[46:49], v[62:65], v[206:209], v[46:49]
	v_mfma_f32_16x16x32_bf16 v[42:45], v[70:73], v[206:209], v[42:45]
	v_mfma_f32_16x16x32_bf16 v[30:33], v[62:65], v[214:217], v[30:33]
	v_mfma_f32_16x16x32_bf16 v[26:29], v[70:73], v[214:217], v[26:29]
	v_mfma_f32_16x16x32_bf16 v[14:17], v[62:65], v[244:247], v[14:17]
	v_mfma_f32_16x16x32_bf16 v[10:13], v[70:73], v[244:247], v[10:13]
	v_mfma_f32_16x16x32_bf16 v[50:53], v[146:149], v[180:183], v[50:53]
	v_mfma_f32_16x16x32_bf16 v[62:65], v[150:153], v[184:187], v[50:53]
	v_mfma_f32_16x16x32_bf16 v[50:53], v[154:157], v[180:183], v[54:57]
	v_mfma_f32_16x16x32_bf16 v[38:41], v[146:149], v[202:205], v[38:41]
	v_mfma_f32_16x16x32_bf16 v[34:37], v[154:157], v[202:205], v[34:37]
	v_mfma_f32_16x16x32_bf16 v[22:25], v[146:149], v[210:213], v[22:25]
	v_mfma_f32_16x16x32_bf16 v[18:21], v[154:157], v[210:213], v[18:21]
	v_mfma_f32_16x16x32_bf16 v[6:9], v[146:149], v[218:221], v[6:9]
	v_mfma_f32_16x16x32_bf16 v[2:5], v[154:157], v[218:221], v[2:5]
	v_mfma_f32_16x16x32_bf16 v[58:61], v[158:161], v[184:187], v[50:53]
	v_mfma_f32_16x16x32_bf16 v[38:41], v[150:153], v[206:209], v[38:41]
	v_mfma_f32_16x16x32_bf16 v[34:37], v[158:161], v[206:209], v[34:37]
	v_mfma_f32_16x16x32_bf16 v[22:25], v[150:153], v[214:217], v[22:25]
	v_mfma_f32_16x16x32_bf16 v[18:21], v[158:161], v[214:217], v[18:21]
	v_mfma_f32_16x16x32_bf16 v[6:9], v[150:153], v[244:247], v[6:9]
	v_mfma_f32_16x16x32_bf16 v[2:5], v[158:161], v[244:247], v[2:5]
	s_barrier
	s_setprio 0
	s_add_i32 s67, s67, 2
	s_add_u32 s62, s62, 0x100
	s_addc_u32 s63, s63, 0
	s_add_u32 s10, s10, 0x10000
	s_addc_u32 s11, s11, 0
	s_cmp_gt_u32 s67, 13
	s_cbranch_scc0 .LBB0_221
	s_and_b64 vcc, exec, s[12:13]
	s_cbranch_vccz .LBB0_224
	s_barrier

.LBB0_309:
	s_add_u32 vcc_lo, s10, 1
	s_addc_u32 vcc_hi, s11, 0
	s_add_u32 s46, s10, 2
	s_addc_u32 s47, s11, 0
	s_lshl_b64 s[48:49], s[46:47], s54
	s_add_u32 s11, s8, s48
	s_addc_u32 s48, s9, s49
	s_cmp_eq_u32 s94, s10
	s_cselect_b32 s50, s0, s11
	s_cselect_b32 s51, s1, s48
	s_cselect_b32 s48, s44, s53
	s_cselect_b32 s49, s45, s63
	s_add_u32 s10, s50, s14
	s_addc_u32 s11, s51, s15
	s_add_i32 s57, 0, 0x10000
	s_add_i32 s60, 0, 0x14000
	v_add_u32_e32 v70, s57, v197
	v_add_u32_e32 v94, s60, v197
	ds_read_b128 v[50:53], v70
	ds_read_b128 v[58:61], v70 offset:1024
	ds_read_b128 v[66:69], v70 offset:2048
	ds_read_b128 v[70:73], v70 offset:3072
	ds_read_b128 v[82:85], v94
	ds_read_b128 v[86:89], v94 offset:1024
	ds_read_b128 v[90:93], v94 offset:2048
	ds_read_b128 v[94:97], v94 offset:3072
	s_lshl_b64 vcc, vcc, s54
	s_add_u32 vcc_lo, s43, vcc_lo
	s_addc_u32 vcc_hi, s52, vcc_hi
	v_lshl_add_u64 v[214:215], vcc, 0, v[202:203]
	s_add_i32 m0, s61, 0xc000
	ds_read_b128 v[154:157], v221
	ds_read_b128 v[158:161], v221 offset:1024
	ds_read_b128 v[170:173], v221 offset:2048
	ds_read_b128 v[174:177], v221 offset:3072
	ds_read_b128 v[178:181], v221 offset:4096
	ds_read_b128 v[182:185], v221 offset:5120
	ds_read_b128 v[186:189], v221 offset:6144
	ds_read_b128 v[210:213], v221 offset:7168
	global_load_lds_dwordx4 v[214:215], off
	v_lshl_add_u64 v[214:215], vcc, 0, v[204:205]
	s_add_i32 m0, s61, 0xe000
	s_nop 0
	global_load_lds_dwordx4 v[214:215], off
	s_waitcnt vmcnt(8)
	s_waitcnt lgkmcnt(0)
	s_setprio 1
	s_barrier
	v_mfma_f32_16x16x32_bf16 v[166:169], v[50:53], v[154:157], v[166:169]
	v_mfma_f32_16x16x32_bf16 v[162:165], v[66:69], v[154:157], v[162:165]
	v_mfma_f32_16x16x32_bf16 v[150:153], v[50:53], v[170:173], v[150:153]
	v_mfma_f32_16x16x32_bf16 v[146:149], v[66:69], v[170:173], v[146:149]
	v_mfma_f32_16x16x32_bf16 v[142:145], v[50:53], v[178:181], v[142:145]
	v_mfma_f32_16x16x32_bf16 v[138:141], v[66:69], v[178:181], v[138:141]
	v_mfma_f32_16x16x32_bf16 v[134:137], v[50:53], v[186:189], v[134:137]
	v_mfma_f32_16x16x32_bf16 v[130:133], v[66:69], v[186:189], v[130:133]
	v_mfma_f32_16x16x32_bf16 v[166:169], v[58:61], v[158:161], v[166:169]
	v_mfma_f32_16x16x32_bf16 v[162:165], v[70:73], v[158:161], v[162:165]
	v_mfma_f32_16x16x32_bf16 v[150:153], v[58:61], v[174:177], v[150:153]
	v_mfma_f32_16x16x32_bf16 v[146:149], v[70:73], v[174:177], v[146:149]
	v_mfma_f32_16x16x32_bf16 v[142:145], v[58:61], v[182:185], v[142:145]
	v_mfma_f32_16x16x32_bf16 v[138:141], v[70:73], v[182:185], v[138:141]
	v_mfma_f32_16x16x32_bf16 v[134:137], v[58:61], v[210:213], v[134:137]
	v_mfma_f32_16x16x32_bf16 v[130:133], v[70:73], v[210:213], v[130:133]
	v_mfma_f32_16x16x32_bf16 v[126:129], v[82:85], v[154:157], v[126:129]
	v_mfma_f32_16x16x32_bf16 v[122:125], v[90:93], v[154:157], v[122:125]
	v_mfma_f32_16x16x32_bf16 v[118:121], v[82:85], v[170:173], v[118:121]
	v_mfma_f32_16x16x32_bf16 v[114:117], v[90:93], v[170:173], v[114:117]
	v_mfma_f32_16x16x32_bf16 v[110:113], v[82:85], v[178:181], v[110:113]
	v_mfma_f32_16x16x32_bf16 v[106:109], v[90:93], v[178:181], v[106:109]
	v_mfma_f32_16x16x32_bf16 v[102:105], v[82:85], v[186:189], v[102:105]
	v_mfma_f32_16x16x32_bf16 v[98:101], v[90:93], v[186:189], v[98:101]
	v_mfma_f32_16x16x32_bf16 v[126:129], v[86:89], v[158:161], v[126:129]
	v_mfma_f32_16x16x32_bf16 v[122:125], v[94:97], v[158:161], v[122:125]
	v_mfma_f32_16x16x32_bf16 v[118:121], v[86:89], v[174:177], v[118:121]
	v_mfma_f32_16x16x32_bf16 v[114:117], v[94:97], v[174:177], v[114:117]
	v_mfma_f32_16x16x32_bf16 v[110:113], v[86:89], v[182:185], v[110:113]
	v_mfma_f32_16x16x32_bf16 v[106:109], v[94:97], v[182:185], v[106:109]
	v_mfma_f32_16x16x32_bf16 v[102:105], v[86:89], v[210:213], v[102:105]
	v_mfma_f32_16x16x32_bf16 v[98:101], v[94:97], v[210:213], v[98:101]
	s_barrier
	s_setprio 0
	s_add_i32 s57, s57, s29
	v_lshl_add_u64 v[214:215], s[48:49], 0, v[190:191]
	s_mov_b32 m0, s57
	ds_read_b128 v[154:157], v221 offset:16384
	ds_read_b128 v[158:161], v221 offset:17408
	ds_read_b128 v[170:173], v221 offset:18432
	ds_read_b128 v[174:177], v221 offset:19456
	ds_read_b128 v[178:181], v221 offset:20480
	ds_read_b128 v[182:185], v221 offset:21504
	ds_read_b128 v[186:189], v221 offset:22528
	ds_read_b128 v[210:213], v221 offset:23552
	global_load_lds_dwordx4 v[214:215], off
	s_add_i32 m0, s57, 0x2000
	v_lshl_add_u64 v[216:217], s[48:49], 0, v[206:207]
	s_add_u32 s48, s48, s2
	s_addc_u32 s49, s49, 0
	s_add_i32 s57, s60, s29
	global_load_lds_dwordx4 v[216:217], off
	v_lshl_add_u64 v[218:219], s[48:49], 0, v[190:191]
	s_mov_b32 m0, s57
	v_lshl_add_u64 v[222:223], s[48:49], 0, v[206:207]
	global_load_lds_dwordx4 v[218:219], off
	s_add_i32 m0, s57, 0x2000
	v_lshl_add_u64 v[234:235], s[50:51], 0, v[202:203]
	global_load_lds_dwordx4 v[222:223], off
	s_mov_b32 m0, s61
	s_nop 0
	global_load_lds_dwordx4 v[234:235], off
	v_lshl_add_u64 v[234:235], s[50:51], 0, v[204:205]
	s_mov_b32 m0, s66
	s_nop 0
	global_load_lds_dwordx4 v[234:235], off
	s_waitcnt vmcnt(8)
	s_waitcnt lgkmcnt(0)
	s_setprio 1
	s_barrier
	v_mfma_f32_16x16x32_bf16 v[78:81], v[50:53], v[154:157], v[78:81]
	v_mfma_f32_16x16x32_bf16 v[74:77], v[66:69], v[154:157], v[74:77]
	v_mfma_f32_16x16x32_bf16 v[62:65], v[50:53], v[170:173], v[62:65]
	v_mfma_f32_16x16x32_bf16 v[54:57], v[66:69], v[170:173], v[54:57]
	v_mfma_f32_16x16x32_bf16 v[46:49], v[50:53], v[178:181], v[46:49]
	v_mfma_f32_16x16x32_bf16 v[42:45], v[66:69], v[178:181], v[42:45]
	v_mfma_f32_16x16x32_bf16 v[38:41], v[50:53], v[186:189], v[38:41]
	v_mfma_f32_16x16x32_bf16 v[34:37], v[66:69], v[186:189], v[34:37]
	v_mfma_f32_16x16x32_bf16 v[78:81], v[58:61], v[158:161], v[78:81]
	v_mfma_f32_16x16x32_bf16 v[74:77], v[70:73], v[158:161], v[74:77]
	v_mfma_f32_16x16x32_bf16 v[62:65], v[58:61], v[174:177], v[62:65]
	v_mfma_f32_16x16x32_bf16 v[54:57], v[70:73], v[174:177], v[54:57]
	v_mfma_f32_16x16x32_bf16 v[46:49], v[58:61], v[182:185], v[46:49]
	v_mfma_f32_16x16x32_bf16 v[42:45], v[70:73], v[182:185], v[42:45]
	v_mfma_f32_16x16x32_bf16 v[38:41], v[58:61], v[210:213], v[38:41]
	v_mfma_f32_16x16x32_bf16 v[34:37], v[70:73], v[210:213], v[34:37]
	v_mfma_f32_16x16x32_bf16 v[30:33], v[82:85], v[154:157], v[30:33]
	v_mfma_f32_16x16x32_bf16 v[26:29], v[90:93], v[154:157], v[26:29]
	v_mfma_f32_16x16x32_bf16 v[22:25], v[82:85], v[170:173], v[22:25]
	v_mfma_f32_16x16x32_bf16 v[18:21], v[90:93], v[170:173], v[18:21]
	v_mfma_f32_16x16x32_bf16 v[14:17], v[82:85], v[178:181], v[14:17]
	v_mfma_f32_16x16x32_bf16 v[10:13], v[90:93], v[178:181], v[10:13]
	v_mfma_f32_16x16x32_bf16 v[6:9], v[82:85], v[186:189], v[6:9]
	v_mfma_f32_16x16x32_bf16 v[2:5], v[90:93], v[186:189], v[2:5]
	v_mfma_f32_16x16x32_bf16 v[30:33], v[86:89], v[158:161], v[30:33]
	v_mfma_f32_16x16x32_bf16 v[26:29], v[94:97], v[158:161], v[26:29]
	v_mfma_f32_16x16x32_bf16 v[22:25], v[86:89], v[174:177], v[22:25]
	v_mfma_f32_16x16x32_bf16 v[18:21], v[94:97], v[174:177], v[18:21]
	v_mfma_f32_16x16x32_bf16 v[14:17], v[86:89], v[182:185], v[14:17]
	v_mfma_f32_16x16x32_bf16 v[10:13], v[94:97], v[182:185], v[10:13]
	v_mfma_f32_16x16x32_bf16 v[6:9], v[86:89], v[210:213], v[6:9]
	v_mfma_f32_16x16x32_bf16 v[2:5], v[94:97], v[210:213], v[2:5]
	s_barrier
	s_setprio 0
	s_add_i32 s57, 0, 0x18000
	s_add_i32 s60, 0, 0x1c000
	v_add_u32_e32 v70, s57, v197
	v_add_u32_e32 v94, s60, v197
	ds_read_b128 v[50:53], v70
	ds_read_b128 v[58:61], v70 offset:1024
	ds_read_b128 v[66:69], v70 offset:2048
	ds_read_b128 v[70:73], v70 offset:3072
	ds_read_b128 v[82:85], v94
	ds_read_b128 v[86:89], v94 offset:1024
	ds_read_b128 v[90:93], v94 offset:2048
	ds_read_b128 v[94:97], v94 offset:3072
	s_add_u32 s48, s50, s28
	s_addc_u32 s49, s51, s21
	s_mov_b32 m0, s67
	v_lshl_add_u64 v[234:235], s[48:49], 0, v[202:203]
	ds_read_b128 v[154:157], v221 offset:32768
	ds_read_b128 v[158:161], v221 offset:33792
	ds_read_b128 v[170:173], v221 offset:34816
	ds_read_b128 v[174:177], v221 offset:35840
	ds_read_b128 v[178:181], v221 offset:36864
	ds_read_b128 v[182:185], v221 offset:37888
	ds_read_b128 v[186:189], v221 offset:38912
	ds_read_b128 v[210:213], v221 offset:39936
	global_load_lds_dwordx4 v[234:235], off
	v_lshl_add_u64 v[234:235], s[48:49], 0, v[204:205]
	s_mov_b32 m0, s69
	s_nop 0
	global_load_lds_dwordx4 v[234:235], off
	s_waitcnt vmcnt(8)
	s_waitcnt lgkmcnt(0)
	s_setprio 1
	s_barrier
	v_mfma_f32_16x16x32_bf16 v[166:169], v[50:53], v[154:157], v[166:169]
	v_mfma_f32_16x16x32_bf16 v[162:165], v[66:69], v[154:157], v[162:165]
	v_mfma_f32_16x16x32_bf16 v[150:153], v[50:53], v[170:173], v[150:153]
	v_mfma_f32_16x16x32_bf16 v[146:149], v[66:69], v[170:173], v[146:149]
	v_mfma_f32_16x16x32_bf16 v[142:145], v[50:53], v[178:181], v[142:145]
	v_mfma_f32_16x16x32_bf16 v[138:141], v[66:69], v[178:181], v[138:141]
	v_mfma_f32_16x16x32_bf16 v[134:137], v[50:53], v[186:189], v[134:137]
	v_mfma_f32_16x16x32_bf16 v[130:133], v[66:69], v[186:189], v[130:133]
	v_mfma_f32_16x16x32_bf16 v[166:169], v[58:61], v[158:161], v[166:169]
	v_mfma_f32_16x16x32_bf16 v[162:165], v[70:73], v[158:161], v[162:165]
	v_mfma_f32_16x16x32_bf16 v[150:153], v[58:61], v[174:177], v[150:153]
	v_mfma_f32_16x16x32_bf16 v[146:149], v[70:73], v[174:177], v[146:149]
	v_mfma_f32_16x16x32_bf16 v[142:145], v[58:61], v[182:185], v[142:145]
	v_mfma_f32_16x16x32_bf16 v[138:141], v[70:73], v[182:185], v[138:141]
	v_mfma_f32_16x16x32_bf16 v[134:137], v[58:61], v[210:213], v[134:137]
	v_mfma_f32_16x16x32_bf16 v[130:133], v[70:73], v[210:213], v[130:133]
	v_mfma_f32_16x16x32_bf16 v[126:129], v[82:85], v[154:157], v[126:129]
	v_mfma_f32_16x16x32_bf16 v[122:125], v[90:93], v[154:157], v[122:125]
	v_mfma_f32_16x16x32_bf16 v[118:121], v[82:85], v[170:173], v[118:121]
	v_mfma_f32_16x16x32_bf16 v[114:117], v[90:93], v[170:173], v[114:117]
	v_mfma_f32_16x16x32_bf16 v[110:113], v[82:85], v[178:181], v[110:113]
	v_mfma_f32_16x16x32_bf16 v[106:109], v[90:93], v[178:181], v[106:109]
	v_mfma_f32_16x16x32_bf16 v[102:105], v[82:85], v[186:189], v[102:105]
	v_mfma_f32_16x16x32_bf16 v[98:101], v[90:93], v[186:189], v[98:101]
	v_mfma_f32_16x16x32_bf16 v[126:129], v[86:89], v[158:161], v[126:129]
	v_mfma_f32_16x16x32_bf16 v[122:125], v[94:97], v[158:161], v[122:125]
	v_mfma_f32_16x16x32_bf16 v[118:121], v[86:89], v[174:177], v[118:121]
	v_mfma_f32_16x16x32_bf16 v[114:117], v[94:97], v[174:177], v[114:117]
	v_mfma_f32_16x16x32_bf16 v[110:113], v[86:89], v[182:185], v[110:113]
	v_mfma_f32_16x16x32_bf16 v[106:109], v[94:97], v[182:185], v[106:109]
	v_mfma_f32_16x16x32_bf16 v[102:105], v[86:89], v[210:213], v[102:105]
	v_mfma_f32_16x16x32_bf16 v[98:101], v[94:97], v[210:213], v[98:101]
	s_barrier
	s_setprio 0
	s_add_i32 s48, s57, s29
	v_lshl_add_u64 v[214:215], v[214:215], 0, s[64:65]
	s_mov_b32 m0, s48
	ds_read_b128 v[154:157], v221 offset:49152
	ds_read_b128 v[158:161], v221 offset:50176
	ds_read_b128 v[170:173], v221 offset:51200
	ds_read_b128 v[174:177], v221 offset:52224
	ds_read_b128 v[178:181], v221 offset:53248
	ds_read_b128 v[182:185], v221 offset:54272
	ds_read_b128 v[186:189], v221 offset:55296
	ds_read_b128 v[210:213], v221 offset:56320
	global_load_lds_dwordx4 v[214:215], off
	v_lshl_add_u64 v[214:215], v[216:217], 0, s[64:65]
	s_add_i32 m0, s48, 0x2000
	s_add_i32 s48, s60, s29
	global_load_lds_dwordx4 v[214:215], off
	v_lshl_add_u64 v[214:215], v[218:219], 0, s[64:65]
	s_mov_b32 m0, s48
	s_nop 0
	global_load_lds_dwordx4 v[214:215], off
	v_lshl_add_u64 v[214:215], v[222:223], 0, s[64:65]
	s_add_i32 m0, s48, 0x2000
	s_nop 0
	global_load_lds_dwordx4 v[214:215], off
	v_lshl_add_u64 v[214:215], s[10:11], 0, v[202:203]
	s_mov_b32 m0, s89
	s_nop 0
	global_load_lds_dwordx4 v[214:215], off
	v_lshl_add_u64 v[214:215], s[10:11], 0, v[204:205]
	s_mov_b32 m0, s91
	s_nop 0
	global_load_lds_dwordx4 v[214:215], off
	s_waitcnt vmcnt(8)
	s_waitcnt lgkmcnt(0)
	s_setprio 1
	s_barrier
	v_mfma_f32_16x16x32_bf16 v[78:81], v[50:53], v[154:157], v[78:81]
	v_mfma_f32_16x16x32_bf16 v[74:77], v[66:69], v[154:157], v[74:77]
	v_mfma_f32_16x16x32_bf16 v[62:65], v[50:53], v[170:173], v[62:65]
	v_mfma_f32_16x16x32_bf16 v[54:57], v[66:69], v[170:173], v[54:57]
	v_mfma_f32_16x16x32_bf16 v[46:49], v[50:53], v[178:181], v[46:49]
	v_mfma_f32_16x16x32_bf16 v[42:45], v[66:69], v[178:181], v[42:45]
	v_mfma_f32_16x16x32_bf16 v[38:41], v[50:53], v[186:189], v[38:41]
	v_mfma_f32_16x16x32_bf16 v[34:37], v[66:69], v[186:189], v[34:37]
	v_mfma_f32_16x16x32_bf16 v[78:81], v[58:61], v[158:161], v[78:81]
	v_mfma_f32_16x16x32_bf16 v[74:77], v[70:73], v[158:161], v[74:77]
	v_mfma_f32_16x16x32_bf16 v[62:65], v[58:61], v[174:177], v[62:65]
	v_mfma_f32_16x16x32_bf16 v[54:57], v[70:73], v[174:177], v[54:57]
	v_mfma_f32_16x16x32_bf16 v[46:49], v[58:61], v[182:185], v[46:49]
	v_mfma_f32_16x16x32_bf16 v[42:45], v[70:73], v[182:185], v[42:45]
	v_mfma_f32_16x16x32_bf16 v[38:41], v[58:61], v[210:213], v[38:41]
	v_mfma_f32_16x16x32_bf16 v[34:37], v[70:73], v[210:213], v[34:37]
	v_mfma_f32_16x16x32_bf16 v[30:33], v[82:85], v[154:157], v[30:33]
	v_mfma_f32_16x16x32_bf16 v[26:29], v[90:93], v[154:157], v[26:29]
	v_mfma_f32_16x16x32_bf16 v[22:25], v[82:85], v[170:173], v[22:25]
	v_mfma_f32_16x16x32_bf16 v[18:21], v[90:93], v[170:173], v[18:21]
	v_mfma_f32_16x16x32_bf16 v[14:17], v[82:85], v[178:181], v[14:17]
	v_mfma_f32_16x16x32_bf16 v[10:13], v[90:93], v[178:181], v[10:13]
	v_mfma_f32_16x16x32_bf16 v[6:9], v[82:85], v[186:189], v[6:9]
	v_mfma_f32_16x16x32_bf16 v[2:5], v[90:93], v[186:189], v[2:5]
	v_mfma_f32_16x16x32_bf16 v[30:33], v[86:89], v[158:161], v[30:33]
	v_mfma_f32_16x16x32_bf16 v[26:29], v[94:97], v[158:161], v[26:29]
	v_mfma_f32_16x16x32_bf16 v[22:25], v[86:89], v[174:177], v[22:25]
	v_mfma_f32_16x16x32_bf16 v[18:21], v[94:97], v[174:177], v[18:21]
	v_mfma_f32_16x16x32_bf16 v[14:17], v[86:89], v[182:185], v[14:17]
	v_mfma_f32_16x16x32_bf16 v[10:13], v[94:97], v[182:185], v[10:13]
	v_mfma_f32_16x16x32_bf16 v[6:9], v[86:89], v[210:213], v[6:9]
	v_mfma_f32_16x16x32_bf16 v[2:5], v[94:97], v[210:213], v[2:5]
	s_barrier
	s_setprio 0
	s_add_u32 s53, s53, 0x100
	s_addc_u32 s63, s63, 0
	s_cmp_ge_u32 s46, s71
	s_mov_b64 s[10:11], s[46:47]
	s_cbranch_scc0 .LBB0_309
	s_and_b64 vcc, exec, s[18:19]
	s_cbranch_vccz .LBB0_312
	s_barrier

.LBB0_462:
	s_add_u32 s50, s0, 0x4000
	s_addc_u32 s51, s1, 0
	s_cmp_eq_u32 s82, 12
	s_cselect_b32 s88, s24, s50
	s_cselect_b32 s89, s19, s51
	s_cselect_b32 s80, s47, s48
	s_cselect_b32 s81, s17, s49
	s_add_u32 s50, s88, 0x8000
	s_addc_u32 s51, s89, 0
	s_add_i32 s83, 0, 0x10000
	s_add_i32 s85, 0, 0x14000
	v_add_u32_e32 v94, s83, v165
	v_add_u32_e32 v164, s85, v165
	ds_read_b128 v[82:85], v94
	ds_read_b128 v[86:89], v94 offset:1024
	ds_read_b128 v[90:93], v94 offset:2048
	ds_read_b128 v[94:97], v94 offset:3072
	ds_read_b128 v[172:175], v164
	ds_read_b128 v[176:179], v164 offset:1024
	ds_read_b128 v[180:183], v164 offset:2048
	ds_read_b128 v[184:187], v164 offset:3072
	v_lshl_add_u64 v[168:169], s[0:1], 0, v[160:161]
	s_add_i32 m0, s29, 0xc000
	ds_read_b128 v[202:205], v167
	ds_read_b128 v[206:209], v167 offset:1024
	ds_read_b128 v[210:213], v167 offset:2048
	ds_read_b128 v[214:217], v167 offset:3072
	ds_read_b128 v[218:221], v167 offset:4096
	ds_read_b128 v[242:245], v167 offset:5120
	ds_read_b128 v[246:249], v167 offset:6144
	ds_read_b128 v[250:253], v167 offset:7168
	global_load_lds_dwordx4 v[168:169], off
	v_lshl_add_u64 v[168:169], s[0:1], 0, v[162:163]
	s_add_i32 m0, s29, 0xe000
	s_nop 0
	global_load_lds_dwordx4 v[168:169], off
	s_waitcnt vmcnt(8)
	s_waitcnt lgkmcnt(0)
	s_setprio 1
	s_barrier
	v_mfma_f32_16x16x32_bf16 v[142:145], v[82:85], v[202:205], v[142:145]
	v_mfma_f32_16x16x32_bf16 v[138:141], v[90:93], v[202:205], v[138:141]
	v_mfma_f32_16x16x32_bf16 v[126:129], v[82:85], v[210:213], v[126:129]
	v_mfma_f32_16x16x32_bf16 v[122:125], v[90:93], v[210:213], v[122:125]
	v_mfma_f32_16x16x32_bf16 v[110:113], v[82:85], v[218:221], v[110:113]
	v_mfma_f32_16x16x32_bf16 v[106:109], v[90:93], v[218:221], v[106:109]
	v_mfma_f32_16x16x32_bf16 v[78:81], v[82:85], v[246:249], v[78:81]
	v_mfma_f32_16x16x32_bf16 v[74:77], v[90:93], v[246:249], v[74:77]
	v_mfma_f32_16x16x32_bf16 v[142:145], v[86:89], v[206:209], v[142:145]
	v_mfma_f32_16x16x32_bf16 v[138:141], v[94:97], v[206:209], v[138:141]
	v_mfma_f32_16x16x32_bf16 v[126:129], v[86:89], v[214:217], v[126:129]
	v_mfma_f32_16x16x32_bf16 v[122:125], v[94:97], v[214:217], v[122:125]
	v_mfma_f32_16x16x32_bf16 v[110:113], v[86:89], v[242:245], v[110:113]
	v_mfma_f32_16x16x32_bf16 v[106:109], v[94:97], v[242:245], v[106:109]
	v_mfma_f32_16x16x32_bf16 v[78:81], v[86:89], v[250:253], v[78:81]
	v_mfma_f32_16x16x32_bf16 v[74:77], v[94:97], v[250:253], v[74:77]
	v_mfma_f32_16x16x32_bf16 v[134:137], v[172:175], v[202:205], v[134:137]
	v_mfma_f32_16x16x32_bf16 v[130:133], v[180:183], v[202:205], v[130:133]
	v_mfma_f32_16x16x32_bf16 v[118:121], v[172:175], v[210:213], v[118:121]
	v_mfma_f32_16x16x32_bf16 v[114:117], v[180:183], v[210:213], v[114:117]
	v_mfma_f32_16x16x32_bf16 v[102:105], v[172:175], v[218:221], v[102:105]
	v_mfma_f32_16x16x32_bf16 v[98:101], v[180:183], v[218:221], v[98:101]
	v_mfma_f32_16x16x32_bf16 v[70:73], v[172:175], v[246:249], v[70:73]
	v_mfma_f32_16x16x32_bf16 v[66:69], v[180:183], v[246:249], v[66:69]
	v_mfma_f32_16x16x32_bf16 v[134:137], v[176:179], v[206:209], v[134:137]
	v_mfma_f32_16x16x32_bf16 v[130:133], v[184:187], v[206:209], v[130:133]
	v_mfma_f32_16x16x32_bf16 v[118:121], v[176:179], v[214:217], v[118:121]
	v_mfma_f32_16x16x32_bf16 v[114:117], v[184:187], v[214:217], v[114:117]
	v_mfma_f32_16x16x32_bf16 v[102:105], v[176:179], v[242:245], v[102:105]
	v_mfma_f32_16x16x32_bf16 v[98:101], v[184:187], v[242:245], v[98:101]
	v_mfma_f32_16x16x32_bf16 v[70:73], v[176:179], v[250:253], v[70:73]
	v_mfma_f32_16x16x32_bf16 v[66:69], v[184:187], v[250:253], v[66:69]
	s_barrier
	s_setprio 0
	s_add_i32 s83, s83, s28
	v_lshl_add_u64 v[168:169], s[80:81], 0, v[148:149]
	s_mov_b32 m0, s83
	ds_read_b128 v[202:205], v167 offset:16384
	ds_read_b128 v[206:209], v167 offset:17408
	ds_read_b128 v[210:213], v167 offset:18432
	ds_read_b128 v[214:217], v167 offset:19456
	ds_read_b128 v[218:221], v167 offset:20480
	ds_read_b128 v[242:245], v167 offset:21504
	ds_read_b128 v[246:249], v167 offset:22528
	ds_read_b128 v[250:253], v167 offset:23552
	global_load_lds_dwordx4 v[168:169], off
	s_add_i32 m0, s83, 0x2000
	s_add_u32 s94, s80, 0x40000
	v_lshl_add_u64 v[188:189], s[80:81], 0, v[152:153]
	s_addc_u32 s95, s81, 0
	s_add_i32 s83, s85, s28
	global_load_lds_dwordx4 v[188:189], off
	v_lshl_add_u64 v[222:223], s[94:95], 0, v[148:149]
	s_mov_b32 m0, s83
	s_nop 0
	global_load_lds_dwordx4 v[222:223], off
	v_lshl_add_u64 v[222:223], s[94:95], 0, v[152:153]
	s_add_i32 m0, s83, 0x2000
	s_nop 0
	global_load_lds_dwordx4 v[222:223], off
	v_lshl_add_u64 v[222:223], s[88:89], 0, v[146:147]
	s_mov_b32 m0, s29
	s_nop 0
	global_load_lds_dwordx4 v[222:223], off
	v_lshl_add_u64 v[222:223], s[88:89], 0, v[150:151]
	s_mov_b32 m0, s31
	s_nop 0
	global_load_lds_dwordx4 v[222:223], off
	s_waitcnt vmcnt(8)
	s_waitcnt lgkmcnt(0)
	s_setprio 1
	s_barrier
	v_mfma_f32_16x16x32_bf16 v[62:65], v[82:85], v[202:205], v[62:65]
	v_mfma_f32_16x16x32_bf16 v[58:61], v[90:93], v[202:205], v[58:61]
	v_mfma_f32_16x16x32_bf16 v[46:49], v[82:85], v[210:213], v[46:49]
	v_mfma_f32_16x16x32_bf16 v[42:45], v[90:93], v[210:213], v[42:45]
	v_mfma_f32_16x16x32_bf16 v[30:33], v[82:85], v[218:221], v[30:33]
	v_mfma_f32_16x16x32_bf16 v[26:29], v[90:93], v[218:221], v[26:29]
	v_mfma_f32_16x16x32_bf16 v[14:17], v[82:85], v[246:249], v[14:17]
	v_mfma_f32_16x16x32_bf16 v[10:13], v[90:93], v[246:249], v[10:13]
	v_mfma_f32_16x16x32_bf16 v[62:65], v[86:89], v[206:209], v[62:65]
	v_mfma_f32_16x16x32_bf16 v[58:61], v[94:97], v[206:209], v[58:61]
	v_mfma_f32_16x16x32_bf16 v[46:49], v[86:89], v[214:217], v[46:49]
	v_mfma_f32_16x16x32_bf16 v[42:45], v[94:97], v[214:217], v[42:45]
	v_mfma_f32_16x16x32_bf16 v[30:33], v[86:89], v[242:245], v[30:33]
	v_mfma_f32_16x16x32_bf16 v[26:29], v[94:97], v[242:245], v[26:29]
	v_mfma_f32_16x16x32_bf16 v[14:17], v[86:89], v[250:253], v[14:17]
	v_mfma_f32_16x16x32_bf16 v[10:13], v[94:97], v[250:253], v[10:13]
	v_mfma_f32_16x16x32_bf16 v[54:57], v[172:175], v[202:205], v[54:57]
	v_mfma_f32_16x16x32_bf16 v[50:53], v[180:183], v[202:205], v[50:53]
	v_mfma_f32_16x16x32_bf16 v[38:41], v[172:175], v[210:213], v[38:41]
	v_mfma_f32_16x16x32_bf16 v[34:37], v[180:183], v[210:213], v[34:37]
	v_mfma_f32_16x16x32_bf16 v[22:25], v[172:175], v[218:221], v[22:25]
	v_mfma_f32_16x16x32_bf16 v[18:21], v[180:183], v[218:221], v[18:21]
	v_mfma_f32_16x16x32_bf16 v[6:9], v[172:175], v[246:249], v[6:9]
	v_mfma_f32_16x16x32_bf16 v[2:5], v[180:183], v[246:249], v[2:5]
	v_mfma_f32_16x16x32_bf16 v[54:57], v[176:179], v[206:209], v[54:57]
	v_mfma_f32_16x16x32_bf16 v[50:53], v[184:187], v[206:209], v[50:53]
	v_mfma_f32_16x16x32_bf16 v[38:41], v[176:179], v[214:217], v[38:41]
	v_mfma_f32_16x16x32_bf16 v[34:37], v[184:187], v[214:217], v[34:37]
	v_mfma_f32_16x16x32_bf16 v[22:25], v[176:179], v[242:245], v[22:25]
	v_mfma_f32_16x16x32_bf16 v[18:21], v[184:187], v[242:245], v[18:21]
	v_mfma_f32_16x16x32_bf16 v[6:9], v[176:179], v[250:253], v[6:9]
	v_mfma_f32_16x16x32_bf16 v[2:5], v[184:187], v[250:253], v[2:5]
	s_barrier
	s_setprio 0
	s_add_i32 s83, 0, 0x18000
	s_add_i32 s85, 0, 0x1c000
	v_add_u32_e32 v94, s83, v165
	v_add_u32_e32 v164, s85, v165
	ds_read_b128 v[82:85], v94
	ds_read_b128 v[86:89], v94 offset:1024
	ds_read_b128 v[90:93], v94 offset:2048
	ds_read_b128 v[94:97], v94 offset:3072
	ds_read_b128 v[172:175], v164
	ds_read_b128 v[176:179], v164 offset:1024
	ds_read_b128 v[180:183], v164 offset:2048
	ds_read_b128 v[184:187], v164 offset:3072
	s_add_u32 s88, s88, 0x4000
	s_addc_u32 s89, s89, 0
	s_mov_b32 m0, s33
	v_lshl_add_u64 v[222:223], s[88:89], 0, v[146:147]
	ds_read_b128 v[202:205], v167 offset:32768
	ds_read_b128 v[206:209], v167 offset:33792
	ds_read_b128 v[210:213], v167 offset:34816
	ds_read_b128 v[214:217], v167 offset:35840
	ds_read_b128 v[218:221], v167 offset:36864
	ds_read_b128 v[242:245], v167 offset:37888
	ds_read_b128 v[246:249], v167 offset:38912
	ds_read_b128 v[250:253], v167 offset:39936
	global_load_lds_dwordx4 v[222:223], off
	v_lshl_add_u64 v[222:223], s[88:89], 0, v[150:151]
	s_mov_b32 m0, s36
	s_nop 0
	global_load_lds_dwordx4 v[222:223], off
	s_waitcnt vmcnt(8)
	s_waitcnt lgkmcnt(0)
	s_setprio 1
	s_barrier
	v_mfma_f32_16x16x32_bf16 v[142:145], v[82:85], v[202:205], v[142:145]
	v_mfma_f32_16x16x32_bf16 v[138:141], v[90:93], v[202:205], v[138:141]
	v_mfma_f32_16x16x32_bf16 v[126:129], v[82:85], v[210:213], v[126:129]
	v_mfma_f32_16x16x32_bf16 v[122:125], v[90:93], v[210:213], v[122:125]
	v_mfma_f32_16x16x32_bf16 v[110:113], v[82:85], v[218:221], v[110:113]
	v_mfma_f32_16x16x32_bf16 v[106:109], v[90:93], v[218:221], v[106:109]
	v_mfma_f32_16x16x32_bf16 v[78:81], v[82:85], v[246:249], v[78:81]
	v_mfma_f32_16x16x32_bf16 v[74:77], v[90:93], v[246:249], v[74:77]
	v_mfma_f32_16x16x32_bf16 v[142:145], v[86:89], v[206:209], v[142:145]
	v_mfma_f32_16x16x32_bf16 v[138:141], v[94:97], v[206:209], v[138:141]
	v_mfma_f32_16x16x32_bf16 v[126:129], v[86:89], v[214:217], v[126:129]
	v_mfma_f32_16x16x32_bf16 v[122:125], v[94:97], v[214:217], v[122:125]
	v_mfma_f32_16x16x32_bf16 v[110:113], v[86:89], v[242:245], v[110:113]
	v_mfma_f32_16x16x32_bf16 v[106:109], v[94:97], v[242:245], v[106:109]
	v_mfma_f32_16x16x32_bf16 v[78:81], v[86:89], v[250:253], v[78:81]
	v_mfma_f32_16x16x32_bf16 v[74:77], v[94:97], v[250:253], v[74:77]
	v_mfma_f32_16x16x32_bf16 v[134:137], v[172:175], v[202:205], v[134:137]
	v_mfma_f32_16x16x32_bf16 v[130:133], v[180:183], v[202:205], v[130:133]
	v_mfma_f32_16x16x32_bf16 v[118:121], v[172:175], v[210:213], v[118:121]
	v_mfma_f32_16x16x32_bf16 v[114:117], v[180:183], v[210:213], v[114:117]
	v_mfma_f32_16x16x32_bf16 v[102:105], v[172:175], v[218:221], v[102:105]
	v_mfma_f32_16x16x32_bf16 v[98:101], v[180:183], v[218:221], v[98:101]
	v_mfma_f32_16x16x32_bf16 v[70:73], v[172:175], v[246:249], v[70:73]
	v_mfma_f32_16x16x32_bf16 v[66:69], v[180:183], v[246:249], v[66:69]
	v_mfma_f32_16x16x32_bf16 v[134:137], v[176:179], v[206:209], v[134:137]
	v_mfma_f32_16x16x32_bf16 v[130:133], v[184:187], v[206:209], v[130:133]
	v_mfma_f32_16x16x32_bf16 v[118:121], v[176:179], v[214:217], v[118:121]
	v_mfma_f32_16x16x32_bf16 v[114:117], v[184:187], v[214:217], v[114:117]
	v_mfma_f32_16x16x32_bf16 v[102:105], v[176:179], v[242:245], v[102:105]
	v_mfma_f32_16x16x32_bf16 v[98:101], v[184:187], v[242:245], v[98:101]
	v_mfma_f32_16x16x32_bf16 v[70:73], v[176:179], v[250:253], v[70:73]
	v_mfma_f32_16x16x32_bf16 v[66:69], v[184:187], v[250:253], v[66:69]
	s_barrier
	s_setprio 0
	s_add_i32 s83, s83, s28
	v_lshl_add_u64 v[168:169], v[168:169], 0, s[64:65]
	s_mov_b32 m0, s83
	ds_read_b128 v[202:205], v167 offset:49152
	ds_read_b128 v[206:209], v167 offset:50176
	ds_read_b128 v[210:213], v167 offset:51200
	ds_read_b128 v[214:217], v167 offset:52224
	ds_read_b128 v[218:221], v167 offset:53248
	ds_read_b128 v[242:245], v167 offset:54272
	ds_read_b128 v[246:249], v167 offset:55296
	ds_read_b128 v[250:253], v167 offset:56320
	global_load_lds_dwordx4 v[168:169], off
	s_add_i32 m0, s83, 0x2000
	s_add_u32 s80, s80, 0x40080
	v_lshl_add_u64 v[168:169], v[188:189], 0, s[64:65]
	s_addc_u32 s81, s81, 0
	s_add_i32 s83, s85, s28
	global_load_lds_dwordx4 v[168:169], off
	v_lshl_add_u64 v[168:169], s[80:81], 0, v[148:149]
	s_mov_b32 m0, s83
	s_nop 0
	global_load_lds_dwordx4 v[168:169], off
	v_lshl_add_u64 v[168:169], s[80:81], 0, v[152:153]
	s_add_i32 m0, s83, 0x2000
	s_nop 0
	global_load_lds_dwordx4 v[168:169], off
	v_lshl_add_u64 v[168:169], s[50:51], 0, v[146:147]
	s_mov_b32 m0, s53
	s_nop 0
	global_load_lds_dwordx4 v[168:169], off
	v_lshl_add_u64 v[168:169], s[50:51], 0, v[150:151]
	s_mov_b32 m0, s54
	s_nop 0
	global_load_lds_dwordx4 v[168:169], off
	s_waitcnt vmcnt(8)
	s_waitcnt lgkmcnt(0)
	s_setprio 1
	s_barrier
	v_mfma_f32_16x16x32_bf16 v[62:65], v[82:85], v[202:205], v[62:65]
	v_mfma_f32_16x16x32_bf16 v[58:61], v[90:93], v[202:205], v[58:61]
	v_mfma_f32_16x16x32_bf16 v[46:49], v[82:85], v[210:213], v[46:49]
	v_mfma_f32_16x16x32_bf16 v[42:45], v[90:93], v[210:213], v[42:45]
	v_mfma_f32_16x16x32_bf16 v[30:33], v[82:85], v[218:221], v[30:33]
	v_mfma_f32_16x16x32_bf16 v[26:29], v[90:93], v[218:221], v[26:29]
	v_mfma_f32_16x16x32_bf16 v[14:17], v[82:85], v[246:249], v[14:17]
	v_mfma_f32_16x16x32_bf16 v[10:13], v[90:93], v[246:249], v[10:13]
	v_mfma_f32_16x16x32_bf16 v[62:65], v[86:89], v[206:209], v[62:65]
	v_mfma_f32_16x16x32_bf16 v[58:61], v[94:97], v[206:209], v[58:61]
	v_mfma_f32_16x16x32_bf16 v[46:49], v[86:89], v[214:217], v[46:49]
	v_mfma_f32_16x16x32_bf16 v[42:45], v[94:97], v[214:217], v[42:45]
	v_mfma_f32_16x16x32_bf16 v[30:33], v[86:89], v[242:245], v[30:33]
	v_mfma_f32_16x16x32_bf16 v[26:29], v[94:97], v[242:245], v[26:29]
	v_mfma_f32_16x16x32_bf16 v[14:17], v[86:89], v[250:253], v[14:17]
	v_mfma_f32_16x16x32_bf16 v[10:13], v[94:97], v[250:253], v[10:13]
	v_mfma_f32_16x16x32_bf16 v[54:57], v[172:175], v[202:205], v[54:57]
	v_mfma_f32_16x16x32_bf16 v[50:53], v[180:183], v[202:205], v[50:53]
	v_mfma_f32_16x16x32_bf16 v[38:41], v[172:175], v[210:213], v[38:41]
	v_mfma_f32_16x16x32_bf16 v[34:37], v[180:183], v[210:213], v[34:37]
	v_mfma_f32_16x16x32_bf16 v[22:25], v[172:175], v[218:221], v[22:25]
	v_mfma_f32_16x16x32_bf16 v[18:21], v[180:183], v[218:221], v[18:21]
	v_mfma_f32_16x16x32_bf16 v[6:9], v[172:175], v[246:249], v[6:9]
	v_mfma_f32_16x16x32_bf16 v[2:5], v[180:183], v[246:249], v[2:5]
	v_mfma_f32_16x16x32_bf16 v[54:57], v[176:179], v[206:209], v[54:57]
	v_mfma_f32_16x16x32_bf16 v[50:53], v[184:187], v[206:209], v[50:53]
	v_mfma_f32_16x16x32_bf16 v[38:41], v[176:179], v[214:217], v[38:41]
	v_mfma_f32_16x16x32_bf16 v[34:37], v[184:187], v[214:217], v[34:37]
	v_mfma_f32_16x16x32_bf16 v[22:25], v[176:179], v[242:245], v[22:25]
	v_mfma_f32_16x16x32_bf16 v[18:21], v[184:187], v[242:245], v[18:21]
	v_mfma_f32_16x16x32_bf16 v[6:9], v[176:179], v[250:253], v[6:9]
	v_mfma_f32_16x16x32_bf16 v[2:5], v[184:187], v[250:253], v[2:5]
	s_barrier
	s_setprio 0
	s_add_i32 s82, s82, 2
	s_add_u32 s48, s48, 0x100
	s_addc_u32 s49, s49, 0
	s_add_u32 s0, s0, 0x10000
	s_addc_u32 s1, s1, 0
	s_cmp_gt_u32 s82, 13
	s_cbranch_scc0 .LBB0_462
	s_and_b64 vcc, exec, s[14:15]
	s_cbranch_vccz .LBB0_465
	s_barrier
